# P7 modulation: all norm2_g/shift/scale loads of an iteration issued at the loop top (20 in flight, counted waits) instead of load-wait-compute per block
# speedup vs baseline: 1.0209x; 1.0143x over previous
; DI float bf_lo(unsigned u) { return __uint_as_float(u << 16); }
; DI float bf_hi(unsigned u) { return __uint_as_float(u & 0xffff0000u); }
; DI void phase7(const Params& p, char* smem) {
;     ...
;   for (int R0 = gw; R0 < NT; R0 += 2 * nw) {
;     const int R1 = R0 + nw;
;     const bool has1 = R1 < NT;
;     const bf16_t* src0 = p.x1b + (size_t)R0 * DM;
;     const bf16_t* src1 = p.x1b + (size_t)(has1 ? R1 : R0) * DM;
;     const float* md0 = p.mod + (R0 >> 11) * 6144;
;     const float* md1 = p.mod + ((has1 ? R1 : R0) >> 11) * 6144;
;     float4 v0[4], v1[4]; float s0 = 0.f, s1 = 0.f;
; #pragma unroll
;     for (int i = 0; i < 4; ++i) {
;       const uint2 u0 = *(const uint2*)(src0 + lane * 4 + 256 * i), u1 = *(const uint2*)(src1 + lane * 4 + 256 * i);
;       v0[i] = make_float4(bf_lo(u0.x), bf_hi(u0.x), bf_lo(u0.y), bf_hi(u0.y)); v1[i] = make_float4(bf_lo(u1.x), bf_hi(u1.x), bf_lo(u1.y), bf_hi(u1.y));
;     }
; #pragma unroll
;     for (int i = 0; i < 4; ++i) { s0 += v0[i].x * v0[i].x + v0[i].y * v0[i].y + v0[i].z * v0[i].z + v0[i].w * v0[i].w; s1 += v1[i].x * v1[i].x + v1[i].y * v1[i].y + v1[i].z * v1[i].z + v1[i].w * v1[i].w; }
;     s0 = wave_sum(s0); s1 = wave_sum(s1);
;     const float r0 = rsqrtf(s0 * (1.f / DM) + EPS), r1 = rsqrtf(s1 * (1.f / DM) + EPS);
; #pragma unroll
;     for (int i = 0; i < 4; ++i) {
;       const int d = lane * 4 + 256 * i;
;       const float4 g = *(const float4*)(p.norm2_g + d);
;       {
;         const float4 sh = *(const float4*)(md0 + 3072 + d), sc = *(const float4*)(md0 + 4096 + d);
;         v0[i].x = v0[i].x * r0 * g.x * (1.f + sc.x) + sh.x; v0[i].y = v0[i].y * r0 * g.y * (1.f + sc.y) + sh.y;
;         v0[i].z = v0[i].z * r0 * g.z * (1.f + sc.z) + sh.z; v0[i].w = v0[i].w * r0 * g.w * (1.f + sc.w) + sh.w;
.LBB0_955:
	v_add_u32_e32 v5, s33, v4
	v_cmp_gt_i32_e64 s[14:15], s35, v5
	v_lshl_add_u64 v[0:1], v[24:25], 0, v[20:21]
	global_load_dwordx2 v[32:33], v[0:1], off
	global_load_dwordx2 v[34:35], v[0:1], off offset:512
	global_load_dwordx2 v[36:37], v[0:1], off offset:1024
	global_load_dwordx2 v[38:39], v[0:1], off offset:1536
	v_cndmask_b32_e64 v70, v4, v5, s[14:15]
	v_ashrrev_i32_e32 v71, 31, v70
	v_lshlrev_b64 v[0:1], 11, v[70:71]
	v_lshl_add_u64 v[0:1], v[16:17], 0, v[0:1]
	global_load_dwordx2 v[40:41], v[0:1], off
	global_load_dwordx2 v[74:75], v[0:1], off offset:512
	global_load_dwordx2 v[82:83], v[0:1], off offset:1024
	global_load_dwordx2 v[86:87], v[0:1], off offset:1536
	v_ashrrev_i32_e32 v6, 11, v4
	v_mul_i32_i24_e32 v42, 0x1800, v6
	v_ashrrev_i32_e32 v43, 31, v42
	v_lshl_add_u64 v[42:43], v[42:43], 2, s[84:85]
	v_lshl_add_u64 v[60:61], v[42:43], 0, s[28:29]
	v_lshl_add_u64 v[62:63], v[42:43], 0, s[30:31]
	v_lshl_add_u64 v[42:43], v[60:61], 0, v[28:29]
	s_waitcnt lgkmcnt(0)
	global_load_dwordx4 v[0:3], v[18:19], off
	v_lshl_add_u64 v[44:45], v[62:63], 0, v[28:29]
	global_load_dwordx4 v[48:51], v[42:43], off
	global_load_dwordx4 v[78:81], v[44:45], off
	v_ashrrev_i32_e32 v6, 11, v70
	v_mul_i32_i24_e32 v70, 0x1800, v6
	v_ashrrev_i32_e32 v71, 31, v70
	v_lshl_add_u64 v[190:191], v[70:71], 2, s[84:85]
	v_lshl_add_u64 v[192:193], v[190:191], 0, s[28:29]
	v_lshl_add_u64 v[190:191], v[190:191], 0, s[30:31]
	v_lshl_add_u64 v[192:193], v[192:193], 0, v[28:29]
	v_lshl_add_u64 v[190:191], v[190:191], 0, v[28:29]
	global_load_dwordx4 v[158:161], v[190:191], off
	global_load_dwordx4 v[174:177], v[192:193], off
	global_load_dwordx4 v[114:117], v[18:19], off offset:1024
	global_load_dwordx4 v[130:133], v[44:45], off offset:1024
	global_load_dwordx4 v[146:149], v[42:43], off offset:1024
	global_load_dwordx4 v[162:165], v[190:191], off offset:1024
	global_load_dwordx4 v[178:181], v[192:193], off offset:1024
	global_load_dwordx4 v[118:121], v[18:19], off offset:2048
	global_load_dwordx4 v[134:137], v[44:45], off offset:2048
	global_load_dwordx4 v[150:153], v[42:43], off offset:2048
	global_load_dwordx4 v[166:169], v[190:191], off offset:2048
	global_load_dwordx4 v[182:185], v[192:193], off offset:2048
	global_load_dwordx4 v[122:125], v[18:19], off offset:3072
	global_load_dwordx4 v[138:141], v[44:45], off offset:3072
	global_load_dwordx4 v[154:157], v[42:43], off offset:3072
	global_load_dwordx4 v[170:173], v[190:191], off offset:3072
	global_load_dwordx4 v[186:189], v[192:193], off offset:3072
	s_waitcnt vmcnt(27)
	v_lshlrev_b32_e32 v88, 16, v32
	v_and_b32_e32 v89, 0xffff0000, v32
	s_waitcnt vmcnt(25)
	v_and_b32_e32 v68, 0xffff0000, v36
	s_waitcnt vmcnt(24)
	v_and_b32_e32 v67, 0xffff0000, v38
	v_lshlrev_b32_e32 v66, 16, v38
	v_mov_b32_e32 v69, v67
	v_lshlrev_b32_e32 v90, 16, v33
	v_and_b32_e32 v91, 0xffff0000, v33
	v_lshlrev_b32_e32 v58, 16, v36
	v_lshlrev_b32_e32 v56, 16, v37
	v_and_b32_e32 v72, 0xffff0000, v37
	v_mov_b32_e32 v59, v66
	v_pk_mul_f32 v[32:33], v[68:69], v[68:69]
	s_waitcnt vmcnt(23)
	v_lshlrev_b32_e32 v42, 16, v41
	v_and_b32_e32 v43, 0xffff0000, v41
	s_waitcnt vmcnt(21)
	v_and_b32_e32 v41, 0xffff0000, v82
	s_waitcnt vmcnt(20)
	v_and_b32_e32 v37, 0xffff0000, v86
	v_lshlrev_b32_e32 v64, 16, v39
	v_pk_fma_f32 v[94:95], v[58:59], v[58:59], v[32:33]
	v_lshlrev_b32_e32 v46, 16, v40
	v_and_b32_e32 v47, 0xffff0000, v40
	v_and_b32_e32 v45, 0xffff0000, v74
	v_lshlrev_b32_e32 v40, 16, v82
	v_lshlrev_b32_e32 v36, 16, v86
	v_lshlrev_b32_e32 v32, 16, v87
	v_and_b32_e32 v33, 0xffff0000, v87
	v_mov_b32_e32 v86, v41
	v_mov_b32_e32 v87, v37
	v_lshlrev_b32_e32 v54, 16, v34
	v_and_b32_e32 v55, 0xffff0000, v34
	v_lshlrev_b32_e32 v52, 16, v35
	v_and_b32_e32 v53, 0xffff0000, v35
	v_mov_b32_e32 v57, v64
	v_lshlrev_b32_e32 v44, 16, v74
	v_lshlrev_b32_e32 v34, 16, v83
	v_and_b32_e32 v35, 0xffff0000, v83
	v_mov_b32_e32 v82, v40
	v_mov_b32_e32 v83, v36
	v_mov_b32_e32 v100, v47
	v_mov_b32_e32 v101, v45
	v_pk_mul_f32 v[86:87], v[86:87], v[86:87]
	v_and_b32_e32 v65, 0xffff0000, v39
	v_lshlrev_b32_e32 v38, 16, v75
	v_and_b32_e32 v39, 0xffff0000, v75
	v_pk_fma_f32 v[74:75], v[56:57], v[56:57], v[94:95]
	v_mov_b32_e32 v94, v34
	v_mov_b32_e32 v95, v32
	v_mov_b32_e32 v98, v46
	v_mov_b32_e32 v99, v44
	v_pk_mul_f32 v[100:101], v[100:101], v[100:101]
	v_pk_fma_f32 v[82:83], v[82:83], v[82:83], v[86:87]
	v_mov_b32_e32 v96, v35
	v_mov_b32_e32 v97, v33
	v_pk_fma_f32 v[86:87], v[98:99], v[98:99], v[100:101]
	v_pk_fma_f32 v[82:83], v[94:95], v[94:95], v[82:83]
	v_mov_b32_e32 v98, v89
	v_mov_b32_e32 v99, v55
	v_pk_fma_f32 v[82:83], v[96:97], v[96:97], v[82:83]
	v_mov_b32_e32 v96, v88
	v_mov_b32_e32 v97, v54
	v_pk_mul_f32 v[98:99], v[98:99], v[98:99]
	v_mov_b32_e32 v92, v90
	v_mov_b32_e32 v102, v42
	v_mov_b32_e32 v103, v38
	v_mov_b32_e32 v93, v52
	v_pk_fma_f32 v[96:97], v[96:97], v[96:97], v[98:99]
	v_mov_b32_e32 v104, v43
	v_mov_b32_e32 v105, v39
	v_pk_fma_f32 v[86:87], v[102:103], v[102:103], v[86:87]
	v_mov_b32_e32 v94, v91
	v_mov_b32_e32 v95, v53
	v_pk_fma_f32 v[92:93], v[92:93], v[92:93], v[96:97]
	v_mov_b32_e32 v73, v65
	v_pk_fma_f32 v[86:87], v[104:105], v[104:105], v[86:87]
	v_pk_fma_f32 v[92:93], v[94:95], v[94:95], v[92:93]
	v_pk_fma_f32 v[74:75], v[72:73], v[72:73], v[74:75]
	v_mov_b32_e32 v94, v86
	v_mov_b32_e32 v95, v92
	v_mov_b32_e32 v92, v87
	v_pk_add_f32 v[86:87], v[94:95], v[92:93]
	v_mov_b32_e32 v92, v82
	v_mov_b32_e32 v93, v74
	v_pk_add_f32 v[86:87], v[86:87], v[92:93]
	v_mov_b32_e32 v74, v83
	v_pk_add_f32 v[74:75], v[86:87], v[74:75]
	ds_bpermute_b32 v82, v11, v74
	ds_bpermute_b32 v83, v11, v75
	s_waitcnt vmcnt(17)
; DI unsigned pk_bf16(float lo, float hi) { f32x2v v = {lo, hi}; bf16x2v b = __builtin_convertvector(v, bf16x2v); return __builtin_bit_cast(unsigned, b); }
; DI void phase7(const Params& p, char* smem) {
;     ...
;     s0 = wave_sum(s0); s1 = wave_sum(s1);
;     const float r0 = rsqrtf(s0 * (1.f / DM) + EPS), r1 = rsqrtf(s1 * (1.f / DM) + EPS);
; #pragma unroll
;     for (int i = 0; i < 4; ++i) {
;       const int d = lane * 4 + 256 * i;
;       const float4 g = *(const float4*)(p.norm2_g + d);
;       {
;         const float4 sh = *(const float4*)(md0 + 3072 + d), sc = *(const float4*)(md0 + 4096 + d);
;         v0[i].x = v0[i].x * r0 * g.x * (1.f + sc.x) + sh.x; v0[i].y = v0[i].y * r0 * g.y * (1.f + sc.y) + sh.y;
;         v0[i].z = v0[i].z * r0 * g.z * (1.f + sc.z) + sh.z; v0[i].w = v0[i].w * r0 * g.w * (1.f + sc.w) + sh.w;
;         uint2 o; o.x = pk_bf16(v0[i].x, v0[i].y); o.y = pk_bf16(v0[i].z, v0[i].w);
;         *(uint2*)(p.h2 + (size_t)R0 * DM + d) = o;
;       }
;       if (has1) {
;         const float4 sh = *(const float4*)(md1 + 3072 + d), sc = *(const float4*)(md1 + 4096 + d);
;         v1[i].x = v1[i].x * r1 * g.x * (1.f + sc.x) + sh.x; v1[i].y = v1[i].y * r1 * g.y * (1.f + sc.y) + sh.y;
;         v1[i].z = v1[i].z * r1 * g.z * (1.f + sc.z) + sh.z; v1[i].w = v1[i].w * r1 * g.w * (1.f + sc.w) + sh.w;
;         uint2 o; o.x = pk_bf16(v1[i].x, v1[i].y); o.y = pk_bf16(v1[i].z, v1[i].w);
;         *(uint2*)(p.h2 + (size_t)R1 * DM + d) = o;
;       }
;     }
	v_pk_add_f32 v[78:79], v[78:79], 1.0 op_sel_hi:[1,0]
	v_pk_add_f32 v[80:81], v[80:81], 1.0 op_sel_hi:[1,0]
	s_waitcnt lgkmcnt(0)
	v_pk_add_f32 v[74:75], v[74:75], v[82:83]
	ds_bpermute_b32 v82, v13, v74
	ds_bpermute_b32 v83, v13, v75
	s_waitcnt lgkmcnt(0)
	v_pk_add_f32 v[74:75], v[74:75], v[82:83]
	ds_bpermute_b32 v82, v15, v74
	ds_bpermute_b32 v83, v15, v75
	s_waitcnt lgkmcnt(0)
	v_pk_add_f32 v[74:75], v[74:75], v[82:83]
	ds_bpermute_b32 v82, v31, v74
	ds_bpermute_b32 v83, v31, v75
	s_waitcnt lgkmcnt(0)
	v_pk_add_f32 v[74:75], v[74:75], v[82:83]
	ds_bpermute_b32 v82, v77, v74
	ds_bpermute_b32 v83, v77, v75
	s_waitcnt lgkmcnt(0)
	v_pk_add_f32 v[82:83], v[74:75], v[82:83]
	ds_bpermute_b32 v86, v84, v82
	ds_bpermute_b32 v87, v84, v83
	v_lshl_add_u64 v[74:75], v[70:71], 2, s[84:85]
	v_lshl_add_u64 v[70:71], v[74:75], 0, s[28:29]
	v_lshl_add_u64 v[74:75], v[74:75], 0, s[30:31]
	s_waitcnt lgkmcnt(0)
	v_pk_add_f32 v[82:83], v[82:83], v[86:87]
	s_nop 0
	v_pk_fma_f32 v[82:83], v[82:83], s[34:35], v[30:31] op_sel_hi:[1,0,0]
	s_nop 0
	v_mul_f32_e32 v6, 0x4b800000, v82
	v_cmp_gt_f32_e32 vcc, s23, v82
	v_mul_f32_e32 v9, 0x4b800000, v83
	v_cmp_gt_f32_e64 s[16:17], s23, v83
	v_cndmask_b32_e32 v6, v82, v6, vcc
	v_rsq_f32_e32 v6, v6
	v_cndmask_b32_e64 v9, v83, v9, s[16:17]
	v_rsq_f32_e32 v9, v9
	v_mul_f32_e32 v57, 0x45800000, v6
	v_cndmask_b32_e32 v76, v6, v57, vcc
	v_mul_f32_e32 v6, 0x45800000, v9
	v_cndmask_b32_e64 v82, v9, v6, s[16:17]
	v_pk_mul_f32 v[86:87], v[82:83], v[88:89] op_sel_hi:[0,1]
	v_pk_mul_f32 v[86:87], v[0:1], v[86:87]
	s_nop 0
	v_pk_fma_f32 v[48:49], v[86:87], v[78:79], v[48:49]
	v_pk_mul_f32 v[78:79], v[82:83], v[90:91] op_sel_hi:[0,1]
	v_pk_mul_f32 v[78:79], v[2:3], v[78:79]
	s_nop 0
	v_pk_fma_f32 v[50:51], v[78:79], v[80:81], v[50:51]
	v_cvt_pk_bf16_f32 v78, v48, v49
	v_cvt_pk_bf16_f32 v79, v50, v51
	v_lshl_add_u64 v[80:81], v[26:27], 0, v[20:21]
	global_store_dwordx2 v[80:81], v[78:79], off
	v_lshl_add_u64 v[78:79], v[22:23], 0, v[20:21]
	s_and_saveexec_b64 s[16:17], s[14:15]
	s_cbranch_execz .LBB0_957
	s_waitcnt vmcnt(16)
	v_pk_mul_f32 v[46:47], v[76:77], v[46:47] op_sel_hi:[0,1]
	v_pk_mul_f32 v[42:43], v[76:77], v[42:43] op_sel_hi:[0,1]
	v_pk_mul_f32 v[0:1], v[0:1], v[46:47]
	v_pk_mul_f32 v[2:3], v[2:3], v[42:43]
	v_pk_add_f32 v[42:43], v[158:159], 1.0 op_sel_hi:[1,0]
	v_pk_add_f32 v[158:159], v[160:161], 1.0 op_sel_hi:[1,0]
	v_pk_fma_f32 v[46:47], v[0:1], v[42:43], v[174:175]
	v_pk_fma_f32 v[42:43], v[2:3], v[158:159], v[176:177]
	v_cvt_pk_bf16_f32 v0, v46, v47
	v_cvt_pk_bf16_f32 v1, v42, v43
	global_store_dwordx2 v[78:79], v[0:1], off
.LBB0_957:
	s_or_b64 exec, exec, s[16:17]
	s_waitcnt vmcnt(13)
	v_lshlrev_b32_e32 v6, 2, v10
	v_mov_b32_e32 v83, v82
	v_pk_mul_f32 v[54:55], v[82:83], v[54:55]
	v_pk_mul_f32 v[52:53], v[82:83], v[52:53]
	v_pk_mul_f32 v[54:55], v[54:55], v[114:115]
	v_pk_mul_f32 v[52:53], v[52:53], v[116:117]
	v_pk_add_f32 v[130:131], v[130:131], 1.0 op_sel_hi:[1,0]
	v_pk_add_f32 v[132:133], v[132:133], 1.0 op_sel_hi:[1,0]
	v_pk_fma_f32 v[54:55], v[54:55], v[130:131], v[146:147]
	v_pk_fma_f32 v[52:53], v[52:53], v[132:133], v[148:149]
	v_cvt_pk_bf16_f32 v130, v54, v55
	v_cvt_pk_bf16_f32 v131, v52, v53
	global_store_dwordx2 v[80:81], v[130:131], off offset:512
	s_and_saveexec_b64 s[16:17], s[14:15]
	s_cbranch_execz .LBB0_959
	s_waitcnt vmcnt(13)
	v_pk_mul_f32 v[44:45], v[76:77], v[44:45] op_sel_hi:[0,1]
	v_pk_mul_f32 v[38:39], v[76:77], v[38:39] op_sel_hi:[0,1]
	v_pk_mul_f32 v[114:115], v[44:45], v[114:115]
	v_pk_mul_f32 v[116:117], v[38:39], v[116:117]
	v_pk_add_f32 v[38:39], v[162:163], 1.0 op_sel_hi:[1,0]
	v_pk_add_f32 v[162:163], v[164:165], 1.0 op_sel_hi:[1,0]
	v_pk_fma_f32 v[44:45], v[114:115], v[38:39], v[178:179]
	v_pk_fma_f32 v[38:39], v[116:117], v[162:163], v[180:181]
	v_cvt_pk_bf16_f32 v114, v44, v45
	v_cvt_pk_bf16_f32 v115, v38, v39
	global_store_dwordx2 v[78:79], v[114:115], off offset:512
.LBB0_959:
	s_or_b64 exec, exec, s[16:17]
	s_waitcnt vmcnt(9)
	v_lshlrev_b32_e32 v6, 2, v12
	v_mov_b32_e32 v59, v68
	v_mov_b32_e32 v57, v72
	v_pk_mul_f32 v[58:59], v[82:83], v[58:59]
	v_pk_mul_f32 v[56:57], v[82:83], v[56:57]
	v_pk_mul_f32 v[58:59], v[58:59], v[118:119]
	v_pk_mul_f32 v[56:57], v[56:57], v[120:121]
	v_pk_add_f32 v[68:69], v[134:135], 1.0 op_sel_hi:[1,0]
	v_pk_add_f32 v[72:73], v[136:137], 1.0 op_sel_hi:[1,0]
	v_pk_fma_f32 v[58:59], v[58:59], v[68:69], v[150:151]
	v_pk_fma_f32 v[56:57], v[56:57], v[72:73], v[152:153]
	v_cvt_pk_bf16_f32 v68, v58, v59
	v_cvt_pk_bf16_f32 v69, v56, v57
	global_store_dwordx2 v[80:81], v[68:69], off offset:1024
	s_and_saveexec_b64 s[16:17], s[14:15]
	s_cbranch_execz .LBB0_961
	s_waitcnt vmcnt(10)
	v_pk_mul_f32 v[40:41], v[76:77], v[40:41] op_sel_hi:[0,1]
	v_pk_mul_f32 v[34:35], v[76:77], v[34:35] op_sel_hi:[0,1]
	v_pk_mul_f32 v[118:119], v[40:41], v[118:119]
	v_pk_mul_f32 v[120:121], v[34:35], v[120:121]
	v_pk_add_f32 v[34:35], v[166:167], 1.0 op_sel_hi:[1,0]
	v_pk_add_f32 v[68:69], v[168:169], 1.0 op_sel_hi:[1,0]
	v_pk_fma_f32 v[40:41], v[118:119], v[34:35], v[182:183]
	v_pk_fma_f32 v[34:35], v[120:121], v[68:69], v[184:185]
	v_cvt_pk_bf16_f32 v118, v40, v41
	v_cvt_pk_bf16_f32 v119, v34, v35
	global_store_dwordx2 v[78:79], v[118:119], off offset:1024
.LBB0_961:
	s_or_b64 exec, exec, s[16:17]
	s_waitcnt vmcnt(5)
	v_lshlrev_b32_e32 v6, 2, v14
	v_pk_mul_f32 v[60:61], v[82:83], v[66:67]
	v_pk_mul_f32 v[62:63], v[82:83], v[64:65]
	v_pk_mul_f32 v[60:61], v[60:61], v[122:123]
	v_pk_mul_f32 v[64:65], v[62:63], v[124:125]
	v_pk_add_f32 v[62:63], v[138:139], 1.0 op_sel_hi:[1,0]
	v_pk_add_f32 v[66:67], v[140:141], 1.0 op_sel_hi:[1,0]
	v_pk_fma_f32 v[62:63], v[60:61], v[62:63], v[154:155]
	v_pk_fma_f32 v[60:61], v[64:65], v[66:67], v[156:157]
	v_cvt_pk_bf16_f32 v64, v62, v63
	v_cvt_pk_bf16_f32 v65, v60, v61
	global_store_dwordx2 v[80:81], v[64:65], off offset:1536
	s_and_saveexec_b64 s[16:17], s[14:15]
	s_cbranch_execz .LBB0_963
	s_waitcnt vmcnt(7)
	v_pk_mul_f32 v[36:37], v[76:77], v[36:37] op_sel_hi:[0,1]
	v_pk_mul_f32 v[32:33], v[76:77], v[32:33] op_sel_hi:[0,1]
	v_pk_mul_f32 v[122:123], v[36:37], v[122:123]
	v_pk_mul_f32 v[124:125], v[32:33], v[124:125]
	v_pk_add_f32 v[32:33], v[170:171], 1.0 op_sel_hi:[1,0]
	v_pk_add_f32 v[170:171], v[172:173], 1.0 op_sel_hi:[1,0]
	v_pk_fma_f32 v[36:37], v[122:123], v[32:33], v[186:187]
	v_pk_fma_f32 v[32:33], v[124:125], v[170:171], v[188:189]
	v_cvt_pk_bf16_f32 v122, v36, v37
	v_cvt_pk_bf16_f32 v123, v32, v33
	global_store_dwordx2 v[78:79], v[122:123], off offset:1536
